# GEMM K-loops: s_setprio pairs around the MFMA blocks removed
# speedup vs baseline: 1.0085x; 1.0085x over previous
.LBB0_94:
	s_add_u32 s90, s48, 0xfffc0000
	s_addc_u32 s91, s49, -1
	v_lshl_add_u64 v[198:199], s[90:91], 0, v[152:153]
	s_mov_b32 m0, s77
	s_nop 0
	global_load_lds_dwordx4 v[198:199], off
	v_lshl_add_u64 v[198:199], s[90:91], 0, v[148:149]
	s_mov_b32 m0, s78
	s_nop 0
	global_load_lds_dwordx4 v[198:199], off
	s_add_u32 s60, s48, 0xfffc0080
	s_addc_u32 s61, s49, -1
	s_add_i32 s88, 0, 0x10000
	s_cmp_eq_u32 s87, 12
	s_cselect_b32 vcc_hi, s59, s61
	s_cselect_b32 vcc_lo, s83, s60
	v_add_u32_e32 v2, s88, v182
	s_cselect_b32 s61, s95, s86
	s_cselect_b32 s60, s84, s85
	s_add_i32 s90, 0, 0x14000
	ds_read_b128 v[132:135], v2
	ds_read_b128 v[136:139], v2 offset:1024
	ds_read_b128 v[140:143], v2 offset:2048
	ds_read_b128 v[144:147], v2 offset:3072
	v_add_u32_e32 v2, s90, v182
	ds_read_b128 v[162:165], v2
	ds_read_b128 v[166:169], v2 offset:1024
	ds_read_b128 v[170:173], v2 offset:2048
	ds_read_b128 v[174:177], v2 offset:3072
	v_lshl_add_u64 v[198:199], s[48:49], 0, v[158:159]
	s_add_i32 m0, s73, 0xc000
	ds_read_b128 v[178:181], v185
	ds_read_b128 v[186:189], v185 offset:1024
	ds_read_b128 v[190:193], v185 offset:2048
	ds_read_b128 v[194:197], v185 offset:3072
	ds_read_b128 v[208:211], v185 offset:4096
	ds_read_b128 v[212:215], v185 offset:5120
	ds_read_b128 v[216:219], v185 offset:6144
	ds_read_b128 v[220:223], v185 offset:7168
	global_load_lds_dwordx4 v[198:199], off
	v_lshl_add_u64 v[198:199], s[48:49], 0, v[160:161]
	s_add_i32 m0, s73, 0xe000
	s_nop 0
	global_load_lds_dwordx4 v[198:199], off
	s_waitcnt vmcnt(8)
	s_waitcnt lgkmcnt(0)
	s_barrier

	s_waitcnt lgkmcnt(0)
	v_mfma_f32_16x16x32_bf16 v[128:131], v[132:135], v[178:181], v[128:131]
	v_mfma_f32_16x16x32_bf16 v[120:123], v[140:143], v[178:181], v[120:123]
	v_mfma_f32_16x16x32_bf16 v[112:115], v[132:135], v[190:193], v[112:115]
	v_mfma_f32_16x16x32_bf16 v[84:87], v[140:143], v[190:193], v[84:87]
	v_mfma_f32_16x16x32_bf16 v[104:107], v[132:135], v[208:211], v[104:107]
	v_mfma_f32_16x16x32_bf16 v[72:75], v[140:143], v[208:211], v[72:75]
	v_mfma_f32_16x16x32_bf16 v[96:99], v[132:135], v[216:219], v[96:99]
	v_mfma_f32_16x16x32_bf16 v[88:91], v[140:143], v[216:219], v[88:91]
	v_mfma_f32_16x16x32_bf16 v[128:131], v[136:139], v[186:189], v[128:131]
	v_mfma_f32_16x16x32_bf16 v[120:123], v[144:147], v[186:189], v[120:123]
	v_mfma_f32_16x16x32_bf16 v[112:115], v[136:139], v[194:197], v[112:115]
	v_mfma_f32_16x16x32_bf16 v[84:87], v[144:147], v[194:197], v[84:87]
	v_mfma_f32_16x16x32_bf16 v[104:107], v[136:139], v[212:215], v[104:107]
	v_mfma_f32_16x16x32_bf16 v[72:75], v[144:147], v[212:215], v[72:75]
	v_mfma_f32_16x16x32_bf16 v[96:99], v[136:139], v[220:223], v[96:99]
	v_mfma_f32_16x16x32_bf16 v[88:91], v[144:147], v[220:223], v[88:91]


	v_mfma_f32_16x16x32_bf16 v[124:127], v[162:165], v[178:181], v[124:127]
	v_mfma_f32_16x16x32_bf16 v[116:119], v[170:173], v[178:181], v[116:119]
	v_mfma_f32_16x16x32_bf16 v[108:111], v[162:165], v[190:193], v[108:111]
	v_mfma_f32_16x16x32_bf16 v[76:79], v[170:173], v[190:193], v[76:79]
	v_mfma_f32_16x16x32_bf16 v[100:103], v[162:165], v[208:211], v[100:103]
	v_mfma_f32_16x16x32_bf16 v[68:71], v[170:173], v[208:211], v[68:71]
	v_mfma_f32_16x16x32_bf16 v[92:95], v[162:165], v[216:219], v[92:95]
	v_mfma_f32_16x16x32_bf16 v[80:83], v[170:173], v[216:219], v[80:83]
	v_mfma_f32_16x16x32_bf16 v[124:127], v[166:169], v[186:189], v[124:127]
	v_mfma_f32_16x16x32_bf16 v[116:119], v[174:177], v[186:189], v[116:119]
	v_mfma_f32_16x16x32_bf16 v[108:111], v[166:169], v[194:197], v[108:111]
	v_mfma_f32_16x16x32_bf16 v[76:79], v[174:177], v[194:197], v[76:79]
	v_mfma_f32_16x16x32_bf16 v[100:103], v[166:169], v[212:215], v[100:103]
	v_mfma_f32_16x16x32_bf16 v[68:71], v[174:177], v[212:215], v[68:71]
	v_mfma_f32_16x16x32_bf16 v[92:95], v[166:169], v[220:223], v[92:95]
	v_mfma_f32_16x16x32_bf16 v[80:83], v[174:177], v[220:223], v[80:83]

	s_barrier
	s_add_i32 s88, s88, s72
	v_lshl_add_u64 v[198:199], s[60:61], 0, v[150:151]
	s_mov_b32 m0, s88
	ds_read_b128 v[178:181], v185 offset:16384
	ds_read_b128 v[186:189], v185 offset:17408
	ds_read_b128 v[190:193], v185 offset:18432
	ds_read_b128 v[194:197], v185 offset:19456
	ds_read_b128 v[208:211], v185 offset:20480
	ds_read_b128 v[212:215], v185 offset:21504
	ds_read_b128 v[216:219], v185 offset:22528
	ds_read_b128 v[220:223], v185 offset:23552
	global_load_lds_dwordx4 v[198:199], off
	s_add_i32 m0, s88, 0x2000
	s_add_u32 s88, s60, 0x40000
	v_lshl_add_u64 v[204:205], s[60:61], 0, v[0:1]
	s_addc_u32 s89, s61, 0
	s_add_i32 s90, s90, s72
	global_load_lds_dwordx4 v[204:205], off
	v_lshl_add_u64 v[206:207], s[88:89], 0, v[150:151]
	s_mov_b32 m0, s90
	v_lshl_add_u64 v[224:225], vcc, 0, v[148:149]
	global_load_lds_dwordx4 v[206:207], off
	v_lshl_add_u64 v[206:207], s[88:89], 0, v[0:1]
	s_add_i32 m0, s90, 0x2000
	s_nop 0
	global_load_lds_dwordx4 v[206:207], off
	v_lshl_add_u64 v[206:207], vcc, 0, v[152:153]


	s_waitcnt vmcnt(6)
	s_waitcnt lgkmcnt(0)
	s_barrier

	s_waitcnt lgkmcnt(0)
	v_mfma_f32_16x16x32_bf16 v[64:67], v[132:135], v[178:181], v[64:67]
	v_mfma_f32_16x16x32_bf16 v[56:59], v[140:143], v[178:181], v[56:59]
	v_mfma_f32_16x16x32_bf16 v[52:55], v[132:135], v[190:193], v[52:55]
	v_mfma_f32_16x16x32_bf16 v[20:23], v[140:143], v[190:193], v[20:23]
	v_mfma_f32_16x16x32_bf16 v[40:43], v[132:135], v[208:211], v[40:43]
	v_mfma_f32_16x16x32_bf16 v[8:11], v[140:143], v[208:211], v[8:11]
	v_mfma_f32_16x16x32_bf16 v[32:35], v[132:135], v[216:219], v[32:35]
	v_mfma_f32_16x16x32_bf16 v[24:27], v[140:143], v[216:219], v[24:27]
	v_mfma_f32_16x16x32_bf16 v[64:67], v[136:139], v[186:189], v[64:67]
	v_mfma_f32_16x16x32_bf16 v[56:59], v[144:147], v[186:189], v[56:59]
	v_mfma_f32_16x16x32_bf16 v[52:55], v[136:139], v[194:197], v[52:55]
	v_mfma_f32_16x16x32_bf16 v[20:23], v[144:147], v[194:197], v[20:23]
	v_mfma_f32_16x16x32_bf16 v[40:43], v[136:139], v[212:215], v[40:43]
	v_mfma_f32_16x16x32_bf16 v[8:11], v[144:147], v[212:215], v[8:11]
	v_mfma_f32_16x16x32_bf16 v[32:35], v[136:139], v[220:223], v[32:35]
	v_mfma_f32_16x16x32_bf16 v[24:27], v[144:147], v[220:223], v[24:27]


	v_mfma_f32_16x16x32_bf16 v[60:63], v[162:165], v[178:181], v[60:63]
	v_mfma_f32_16x16x32_bf16 v[48:51], v[170:173], v[178:181], v[48:51]
	v_mfma_f32_16x16x32_bf16 v[44:47], v[162:165], v[190:193], v[44:47]
	v_mfma_f32_16x16x32_bf16 v[12:15], v[170:173], v[190:193], v[12:15]
	v_mfma_f32_16x16x32_bf16 v[36:39], v[162:165], v[208:211], v[36:39]
	v_mfma_f32_16x16x32_bf16 v[4:7], v[170:173], v[208:211], v[4:7]
	v_mfma_f32_16x16x32_bf16 v[28:31], v[162:165], v[216:219], v[28:31]
	v_mfma_f32_16x16x32_bf16 v[16:19], v[170:173], v[216:219], v[16:19]
	v_mfma_f32_16x16x32_bf16 v[60:63], v[166:169], v[186:189], v[60:63]
	v_mfma_f32_16x16x32_bf16 v[48:51], v[174:177], v[186:189], v[48:51]
	v_mfma_f32_16x16x32_bf16 v[44:47], v[166:169], v[194:197], v[44:47]
	v_mfma_f32_16x16x32_bf16 v[12:15], v[174:177], v[194:197], v[12:15]
	v_mfma_f32_16x16x32_bf16 v[36:39], v[166:169], v[212:215], v[36:39]
	v_mfma_f32_16x16x32_bf16 v[4:7], v[174:177], v[212:215], v[4:7]
	v_mfma_f32_16x16x32_bf16 v[28:31], v[166:169], v[220:223], v[28:31]
	v_mfma_f32_16x16x32_bf16 v[16:19], v[174:177], v[220:223], v[16:19]

	s_barrier
	s_add_i32 s90, 0, 0x18000
	v_add_u32_e32 v2, s90, v182
	s_add_i32 s91, 0, 0x1c000
	ds_read_b128 v[132:135], v2
	ds_read_b128 v[136:139], v2 offset:1024
	ds_read_b128 v[140:143], v2 offset:2048
	ds_read_b128 v[144:147], v2 offset:3072
	v_add_u32_e32 v2, s91, v182
	ds_read_b128 v[162:165], v2
	ds_read_b128 v[166:169], v2 offset:1024
	ds_read_b128 v[170:173], v2 offset:2048
	ds_read_b128 v[174:177], v2 offset:3072
	s_add_u32 s88, vcc_lo, 0x40000
	s_addc_u32 s89, vcc_hi, 0
	s_mov_b32 m0, s73
	s_nop 0
	global_load_lds_dwordx4 v[206:207], off
	s_mov_b32 m0, s74
	s_nop 0
	global_load_lds_dwordx4 v[224:225], off
	s_mov_b32 m0, s75
	v_lshl_add_u64 v[226:227], s[88:89], 0, v[152:153]
	ds_read_b128 v[178:181], v185 offset:32768
	ds_read_b128 v[186:189], v185 offset:33792
	ds_read_b128 v[190:193], v185 offset:34816
	ds_read_b128 v[194:197], v185 offset:35840
	ds_read_b128 v[208:211], v185 offset:36864
	ds_read_b128 v[212:215], v185 offset:37888
	ds_read_b128 v[216:219], v185 offset:38912
	ds_read_b128 v[220:223], v185 offset:39936
	global_load_lds_dwordx4 v[226:227], off
	v_lshl_add_u64 v[226:227], s[88:89], 0, v[148:149]
	s_mov_b32 m0, s76
	s_nop 0
	global_load_lds_dwordx4 v[226:227], off
	s_waitcnt vmcnt(8)
	s_waitcnt lgkmcnt(0)
	s_barrier

	s_waitcnt lgkmcnt(0)
	v_mfma_f32_16x16x32_bf16 v[128:131], v[132:135], v[178:181], v[128:131]
	v_mfma_f32_16x16x32_bf16 v[120:123], v[140:143], v[178:181], v[120:123]
	v_mfma_f32_16x16x32_bf16 v[112:115], v[132:135], v[190:193], v[112:115]
	v_mfma_f32_16x16x32_bf16 v[84:87], v[140:143], v[190:193], v[84:87]
	v_mfma_f32_16x16x32_bf16 v[104:107], v[132:135], v[208:211], v[104:107]
	v_mfma_f32_16x16x32_bf16 v[72:75], v[140:143], v[208:211], v[72:75]
	v_mfma_f32_16x16x32_bf16 v[96:99], v[132:135], v[216:219], v[96:99]
	v_mfma_f32_16x16x32_bf16 v[88:91], v[140:143], v[216:219], v[88:91]
	v_mfma_f32_16x16x32_bf16 v[128:131], v[136:139], v[186:189], v[128:131]
	v_mfma_f32_16x16x32_bf16 v[120:123], v[144:147], v[186:189], v[120:123]
	v_mfma_f32_16x16x32_bf16 v[112:115], v[136:139], v[194:197], v[112:115]
	v_mfma_f32_16x16x32_bf16 v[84:87], v[144:147], v[194:197], v[84:87]
	v_mfma_f32_16x16x32_bf16 v[104:107], v[136:139], v[212:215], v[104:107]
	v_mfma_f32_16x16x32_bf16 v[72:75], v[144:147], v[212:215], v[72:75]
	v_mfma_f32_16x16x32_bf16 v[96:99], v[136:139], v[220:223], v[96:99]
	v_mfma_f32_16x16x32_bf16 v[88:91], v[144:147], v[220:223], v[88:91]


	v_mfma_f32_16x16x32_bf16 v[124:127], v[162:165], v[178:181], v[124:127]
	v_mfma_f32_16x16x32_bf16 v[116:119], v[170:173], v[178:181], v[116:119]
	v_mfma_f32_16x16x32_bf16 v[108:111], v[162:165], v[190:193], v[108:111]
	v_mfma_f32_16x16x32_bf16 v[76:79], v[170:173], v[190:193], v[76:79]
	v_mfma_f32_16x16x32_bf16 v[100:103], v[162:165], v[208:211], v[100:103]
	v_mfma_f32_16x16x32_bf16 v[68:71], v[170:173], v[208:211], v[68:71]
	v_mfma_f32_16x16x32_bf16 v[92:95], v[162:165], v[216:219], v[92:95]
	v_mfma_f32_16x16x32_bf16 v[80:83], v[170:173], v[216:219], v[80:83]
	v_mfma_f32_16x16x32_bf16 v[124:127], v[166:169], v[186:189], v[124:127]
	v_mfma_f32_16x16x32_bf16 v[116:119], v[174:177], v[186:189], v[116:119]
	v_mfma_f32_16x16x32_bf16 v[108:111], v[166:169], v[194:197], v[108:111]
	v_mfma_f32_16x16x32_bf16 v[76:79], v[174:177], v[194:197], v[76:79]
	v_mfma_f32_16x16x32_bf16 v[100:103], v[166:169], v[212:215], v[100:103]
	v_mfma_f32_16x16x32_bf16 v[68:71], v[174:177], v[212:215], v[68:71]
	v_mfma_f32_16x16x32_bf16 v[92:95], v[166:169], v[220:223], v[92:95]
	v_mfma_f32_16x16x32_bf16 v[80:83], v[174:177], v[220:223], v[80:83]

	s_barrier
	s_add_i32 s88, s90, s72
	v_lshl_add_u64 v[198:199], v[198:199], 0, s[12:13]
	s_mov_b32 m0, s88
	ds_read_b128 v[178:181], v185 offset:49152
	ds_read_b128 v[186:189], v185 offset:50176
	ds_read_b128 v[190:193], v185 offset:51200
	ds_read_b128 v[194:197], v185 offset:52224
	ds_read_b128 v[208:211], v185 offset:53248
	ds_read_b128 v[212:215], v185 offset:54272
	ds_read_b128 v[216:219], v185 offset:55296
	ds_read_b128 v[220:223], v185 offset:56320
	global_load_lds_dwordx4 v[198:199], off
	s_add_i32 m0, s88, 0x2000
	s_add_u32 s60, s60, 0x40080
	v_lshl_add_u64 v[198:199], v[204:205], 0, s[12:13]
	s_addc_u32 s61, s61, 0
	s_add_i32 s88, s91, s72
	global_load_lds_dwordx4 v[198:199], off
	v_lshl_add_u64 v[198:199], s[60:61], 0, v[150:151]
	s_mov_b32 m0, s88
	s_nop 0
	global_load_lds_dwordx4 v[198:199], off
	v_lshl_add_u64 v[198:199], s[60:61], 0, v[0:1]
	s_add_i32 m0, s88, 0x2000
	s_nop 0
	global_load_lds_dwordx4 v[198:199], off


	s_waitcnt vmcnt(6)
	s_waitcnt lgkmcnt(0)
	s_barrier

	s_waitcnt lgkmcnt(0)
	v_mfma_f32_16x16x32_bf16 v[64:67], v[132:135], v[178:181], v[64:67]
	v_mfma_f32_16x16x32_bf16 v[56:59], v[140:143], v[178:181], v[56:59]
	v_mfma_f32_16x16x32_bf16 v[52:55], v[132:135], v[190:193], v[52:55]
	v_mfma_f32_16x16x32_bf16 v[20:23], v[140:143], v[190:193], v[20:23]
	v_mfma_f32_16x16x32_bf16 v[40:43], v[132:135], v[208:211], v[40:43]
	v_mfma_f32_16x16x32_bf16 v[8:11], v[140:143], v[208:211], v[8:11]
	v_mfma_f32_16x16x32_bf16 v[32:35], v[132:135], v[216:219], v[32:35]
	v_mfma_f32_16x16x32_bf16 v[24:27], v[140:143], v[216:219], v[24:27]
	v_mfma_f32_16x16x32_bf16 v[64:67], v[136:139], v[186:189], v[64:67]
	v_mfma_f32_16x16x32_bf16 v[56:59], v[144:147], v[186:189], v[56:59]
	v_mfma_f32_16x16x32_bf16 v[52:55], v[136:139], v[194:197], v[52:55]
	v_mfma_f32_16x16x32_bf16 v[20:23], v[144:147], v[194:197], v[20:23]
	v_mfma_f32_16x16x32_bf16 v[40:43], v[136:139], v[212:215], v[40:43]
	v_mfma_f32_16x16x32_bf16 v[8:11], v[144:147], v[212:215], v[8:11]
	v_mfma_f32_16x16x32_bf16 v[32:35], v[136:139], v[220:223], v[32:35]
	v_mfma_f32_16x16x32_bf16 v[24:27], v[144:147], v[220:223], v[24:27]


	v_mfma_f32_16x16x32_bf16 v[60:63], v[162:165], v[178:181], v[60:63]
	v_mfma_f32_16x16x32_bf16 v[48:51], v[170:173], v[178:181], v[48:51]
	v_mfma_f32_16x16x32_bf16 v[44:47], v[162:165], v[190:193], v[44:47]
	v_mfma_f32_16x16x32_bf16 v[12:15], v[170:173], v[190:193], v[12:15]
	v_mfma_f32_16x16x32_bf16 v[36:39], v[162:165], v[208:211], v[36:39]
	v_mfma_f32_16x16x32_bf16 v[4:7], v[170:173], v[208:211], v[4:7]
	v_mfma_f32_16x16x32_bf16 v[28:31], v[162:165], v[216:219], v[28:31]
	v_mfma_f32_16x16x32_bf16 v[16:19], v[170:173], v[216:219], v[16:19]
	v_mfma_f32_16x16x32_bf16 v[60:63], v[166:169], v[186:189], v[60:63]
	v_mfma_f32_16x16x32_bf16 v[48:51], v[174:177], v[186:189], v[48:51]
	v_mfma_f32_16x16x32_bf16 v[44:47], v[166:169], v[194:197], v[44:47]
	v_mfma_f32_16x16x32_bf16 v[12:15], v[174:177], v[194:197], v[12:15]
	v_mfma_f32_16x16x32_bf16 v[36:39], v[166:169], v[212:215], v[36:39]
	v_mfma_f32_16x16x32_bf16 v[4:7], v[174:177], v[212:215], v[4:7]
	v_mfma_f32_16x16x32_bf16 v[28:31], v[166:169], v[220:223], v[28:31]
	v_mfma_f32_16x16x32_bf16 v[16:19], v[174:177], v[220:223], v[16:19]

	s_barrier
	s_add_i32 s87, s87, 2
	s_add_u32 s48, s48, 0x100
	s_addc_u32 s49, s49, 0
	s_add_u32 s85, s85, 0x100
	s_addc_u32 s86, s86, 0
	s_cmp_gt_u32 s87, 13
	s_cbranch_scc0 .LBB0_94
	s_and_b64 vcc, exec, s[20:21]
	s_cbranch_vccz .LBB0_97
	s_barrier

.LBB0_685:
	s_add_u32 s82, s46, 0xfff80000
	s_addc_u32 s83, s47, -1
	v_lshl_add_u64 v[200:201], s[82:83], 0, v[134:135]
	s_mov_b32 m0, s71
	s_nop 0
	global_load_lds_dwordx4 v[200:201], off
	v_lshl_add_u64 v[200:201], s[82:83], 0, v[132:133]
	s_mov_b32 m0, s72
	s_nop 0
	global_load_lds_dwordx4 v[200:201], off
	s_add_u32 s48, s46, 0xfff80080
	s_addc_u32 s49, s47, -1
	s_add_i32 s81, 0, 0x10000
	s_cmp_eq_u32 s80, 28
	s_cselect_b32 s51, s35, s49
	s_cselect_b32 s50, s76, s48
	s_cselect_b32 s49, s21, s79
	s_cselect_b32 s48, s77, s78
	s_add_i32 s84, 0, 0x14000
	v_add_u32_e32 v156, s81, v149
	v_add_u32_e32 v172, s84, v149
	ds_read_b128 v[140:143], v156
	ds_read_b128 v[144:147], v156 offset:1024
	ds_read_b128 v[152:155], v156 offset:2048
	ds_read_b128 v[156:159], v156 offset:3072
	ds_read_b128 v[160:163], v172
	ds_read_b128 v[164:167], v172 offset:1024
	ds_read_b128 v[168:171], v172 offset:2048
	ds_read_b128 v[172:175], v172 offset:3072
	v_lshl_add_u64 v[200:201], s[46:47], 0, v[136:137]
	s_add_i32 m0, s59, 0xc000
	ds_read_b128 v[176:179], v151
	ds_read_b128 v[180:183], v151 offset:1024
	ds_read_b128 v[184:187], v151 offset:2048
	ds_read_b128 v[188:191], v151 offset:3072
	ds_read_b128 v[192:195], v151 offset:4096
	ds_read_b128 v[196:199], v151 offset:5120
	ds_read_b128 v[204:207], v151 offset:6144
	ds_read_b128 v[208:211], v151 offset:7168
	global_load_lds_dwordx4 v[200:201], off
	v_lshl_add_u64 v[200:201], s[46:47], 0, v[138:139]
	s_add_i32 m0, s59, 0xe000
	s_nop 0
	global_load_lds_dwordx4 v[200:201], off
	s_waitcnt vmcnt(8)
	s_waitcnt lgkmcnt(0)
	s_barrier

	s_waitcnt lgkmcnt(0)
	v_mfma_f32_16x16x32_bf16 v[128:131], v[140:143], v[176:179], v[128:131]
	v_mfma_f32_16x16x32_bf16 v[124:127], v[152:155], v[176:179], v[124:127]
	v_mfma_f32_16x16x32_bf16 v[112:115], v[140:143], v[184:187], v[112:115]
	v_mfma_f32_16x16x32_bf16 v[108:111], v[152:155], v[184:187], v[108:111]
	v_mfma_f32_16x16x32_bf16 v[96:99], v[140:143], v[192:195], v[96:99]
	v_mfma_f32_16x16x32_bf16 v[92:95], v[152:155], v[192:195], v[92:95]
	v_mfma_f32_16x16x32_bf16 v[80:83], v[140:143], v[204:207], v[80:83]
	v_mfma_f32_16x16x32_bf16 v[76:79], v[152:155], v[204:207], v[76:79]
	v_mfma_f32_16x16x32_bf16 v[128:131], v[144:147], v[180:183], v[128:131]
	v_mfma_f32_16x16x32_bf16 v[124:127], v[156:159], v[180:183], v[124:127]
	v_mfma_f32_16x16x32_bf16 v[112:115], v[144:147], v[188:191], v[112:115]
	v_mfma_f32_16x16x32_bf16 v[108:111], v[156:159], v[188:191], v[108:111]
	v_mfma_f32_16x16x32_bf16 v[96:99], v[144:147], v[196:199], v[96:99]
	v_mfma_f32_16x16x32_bf16 v[92:95], v[156:159], v[196:199], v[92:95]
	v_mfma_f32_16x16x32_bf16 v[80:83], v[144:147], v[208:211], v[80:83]
	v_mfma_f32_16x16x32_bf16 v[76:79], v[156:159], v[208:211], v[76:79]


	v_mfma_f32_16x16x32_bf16 v[120:123], v[160:163], v[176:179], v[120:123]
	v_mfma_f32_16x16x32_bf16 v[116:119], v[168:171], v[176:179], v[116:119]
	v_mfma_f32_16x16x32_bf16 v[104:107], v[160:163], v[184:187], v[104:107]
	v_mfma_f32_16x16x32_bf16 v[100:103], v[168:171], v[184:187], v[100:103]
	v_mfma_f32_16x16x32_bf16 v[88:91], v[160:163], v[192:195], v[88:91]
	v_mfma_f32_16x16x32_bf16 v[84:87], v[168:171], v[192:195], v[84:87]
	v_mfma_f32_16x16x32_bf16 v[72:75], v[160:163], v[204:207], v[72:75]
	v_mfma_f32_16x16x32_bf16 v[68:71], v[168:171], v[204:207], v[68:71]
	v_mfma_f32_16x16x32_bf16 v[120:123], v[164:167], v[180:183], v[120:123]
	v_mfma_f32_16x16x32_bf16 v[116:119], v[172:175], v[180:183], v[116:119]
	v_mfma_f32_16x16x32_bf16 v[104:107], v[164:167], v[188:191], v[104:107]
	v_mfma_f32_16x16x32_bf16 v[100:103], v[172:175], v[188:191], v[100:103]
	v_mfma_f32_16x16x32_bf16 v[88:91], v[164:167], v[196:199], v[88:91]
	v_mfma_f32_16x16x32_bf16 v[84:87], v[172:175], v[196:199], v[84:87]
	v_mfma_f32_16x16x32_bf16 v[72:75], v[164:167], v[208:211], v[72:75]
	v_mfma_f32_16x16x32_bf16 v[68:71], v[172:175], v[208:211], v[68:71]

	s_barrier
	s_add_i32 s81, s81, s52
	v_lshl_add_u64 v[200:201], s[48:49], 0, v[2:3]
	s_mov_b32 m0, s81
	ds_read_b128 v[176:179], v151 offset:16384
	ds_read_b128 v[180:183], v151 offset:17408
	ds_read_b128 v[184:187], v151 offset:18432
	ds_read_b128 v[188:191], v151 offset:19456
	ds_read_b128 v[192:195], v151 offset:20480
	ds_read_b128 v[196:199], v151 offset:21504
	ds_read_b128 v[204:207], v151 offset:22528
	ds_read_b128 v[208:211], v151 offset:23552
	global_load_lds_dwordx4 v[200:201], off
	s_add_i32 m0, s81, 0x2000
	s_add_u32 s82, s48, 0x80000
	v_lshl_add_u64 v[212:213], s[48:49], 0, v[0:1]
	s_addc_u32 s83, s49, 0
	s_add_i32 s81, s84, s52
	global_load_lds_dwordx4 v[212:213], off
	v_lshl_add_u64 v[214:215], s[82:83], 0, v[2:3]
	s_mov_b32 m0, s81
	v_lshl_add_u64 v[216:217], s[50:51], 0, v[132:133]
	global_load_lds_dwordx4 v[214:215], off
	v_lshl_add_u64 v[214:215], s[82:83], 0, v[0:1]
	s_add_i32 m0, s81, 0x2000
	s_nop 0
	global_load_lds_dwordx4 v[214:215], off
	v_lshl_add_u64 v[214:215], s[50:51], 0, v[134:135]


	s_waitcnt vmcnt(6)
	s_waitcnt lgkmcnt(0)
	s_barrier

	s_waitcnt lgkmcnt(0)
	v_mfma_f32_16x16x32_bf16 v[64:67], v[140:143], v[176:179], v[64:67]
	v_mfma_f32_16x16x32_bf16 v[60:63], v[152:155], v[176:179], v[60:63]
	v_mfma_f32_16x16x32_bf16 v[48:51], v[140:143], v[184:187], v[48:51]
	v_mfma_f32_16x16x32_bf16 v[44:47], v[152:155], v[184:187], v[44:47]
	v_mfma_f32_16x16x32_bf16 v[32:35], v[140:143], v[192:195], v[32:35]
	v_mfma_f32_16x16x32_bf16 v[28:31], v[152:155], v[192:195], v[28:31]
	v_mfma_f32_16x16x32_bf16 v[16:19], v[140:143], v[204:207], v[16:19]
	v_mfma_f32_16x16x32_bf16 v[12:15], v[152:155], v[204:207], v[12:15]
	v_mfma_f32_16x16x32_bf16 v[64:67], v[144:147], v[180:183], v[64:67]
	v_mfma_f32_16x16x32_bf16 v[60:63], v[156:159], v[180:183], v[60:63]
	v_mfma_f32_16x16x32_bf16 v[48:51], v[144:147], v[188:191], v[48:51]
	v_mfma_f32_16x16x32_bf16 v[44:47], v[156:159], v[188:191], v[44:47]
	v_mfma_f32_16x16x32_bf16 v[32:35], v[144:147], v[196:199], v[32:35]
	v_mfma_f32_16x16x32_bf16 v[28:31], v[156:159], v[196:199], v[28:31]
	v_mfma_f32_16x16x32_bf16 v[16:19], v[144:147], v[208:211], v[16:19]
	v_mfma_f32_16x16x32_bf16 v[12:15], v[156:159], v[208:211], v[12:15]


	v_mfma_f32_16x16x32_bf16 v[56:59], v[160:163], v[176:179], v[56:59]
	v_mfma_f32_16x16x32_bf16 v[52:55], v[168:171], v[176:179], v[52:55]
	v_mfma_f32_16x16x32_bf16 v[40:43], v[160:163], v[184:187], v[40:43]
	v_mfma_f32_16x16x32_bf16 v[36:39], v[168:171], v[184:187], v[36:39]
	v_mfma_f32_16x16x32_bf16 v[24:27], v[160:163], v[192:195], v[24:27]
	v_mfma_f32_16x16x32_bf16 v[20:23], v[168:171], v[192:195], v[20:23]
	v_mfma_f32_16x16x32_bf16 v[8:11], v[160:163], v[204:207], v[8:11]
	v_mfma_f32_16x16x32_bf16 v[4:7], v[168:171], v[204:207], v[4:7]
	v_mfma_f32_16x16x32_bf16 v[56:59], v[164:167], v[180:183], v[56:59]
	v_mfma_f32_16x16x32_bf16 v[52:55], v[172:175], v[180:183], v[52:55]
	v_mfma_f32_16x16x32_bf16 v[40:43], v[164:167], v[188:191], v[40:43]
	v_mfma_f32_16x16x32_bf16 v[36:39], v[172:175], v[188:191], v[36:39]
	v_mfma_f32_16x16x32_bf16 v[24:27], v[164:167], v[196:199], v[24:27]
	v_mfma_f32_16x16x32_bf16 v[20:23], v[172:175], v[196:199], v[20:23]
	v_mfma_f32_16x16x32_bf16 v[8:11], v[164:167], v[208:211], v[8:11]
	v_mfma_f32_16x16x32_bf16 v[4:7], v[172:175], v[208:211], v[4:7]

	s_barrier
	s_add_i32 s81, 0, 0x18000
	s_add_i32 s82, 0, 0x1c000
	v_add_u32_e32 v156, s81, v149
	v_add_u32_e32 v172, s82, v149
	ds_read_b128 v[140:143], v156
	ds_read_b128 v[144:147], v156 offset:1024
	ds_read_b128 v[152:155], v156 offset:2048
	ds_read_b128 v[156:159], v156 offset:3072
	ds_read_b128 v[160:163], v172
	ds_read_b128 v[164:167], v172 offset:1024
	ds_read_b128 v[168:171], v172 offset:2048
	ds_read_b128 v[172:175], v172 offset:3072
	s_add_u32 s50, s50, 0x80000
	s_addc_u32 s51, s51, 0
	s_mov_b32 m0, s59
	s_nop 0
	global_load_lds_dwordx4 v[214:215], off
	s_mov_b32 m0, s60
	s_nop 0
	global_load_lds_dwordx4 v[216:217], off
	s_mov_b32 m0, s61
	v_lshl_add_u64 v[218:219], s[50:51], 0, v[134:135]
	ds_read_b128 v[176:179], v151 offset:32768
	ds_read_b128 v[180:183], v151 offset:33792
	ds_read_b128 v[184:187], v151 offset:34816
	ds_read_b128 v[188:191], v151 offset:35840
	ds_read_b128 v[192:195], v151 offset:36864
	ds_read_b128 v[196:199], v151 offset:37888
	ds_read_b128 v[204:207], v151 offset:38912
	ds_read_b128 v[208:211], v151 offset:39936
	global_load_lds_dwordx4 v[218:219], off
	v_lshl_add_u64 v[218:219], s[50:51], 0, v[132:133]
	s_mov_b32 m0, s70
	s_nop 0
	global_load_lds_dwordx4 v[218:219], off
	s_waitcnt vmcnt(8)
	s_waitcnt lgkmcnt(0)
	s_barrier

	s_waitcnt lgkmcnt(0)
	v_mfma_f32_16x16x32_bf16 v[128:131], v[140:143], v[176:179], v[128:131]
	v_mfma_f32_16x16x32_bf16 v[124:127], v[152:155], v[176:179], v[124:127]
	v_mfma_f32_16x16x32_bf16 v[112:115], v[140:143], v[184:187], v[112:115]
	v_mfma_f32_16x16x32_bf16 v[108:111], v[152:155], v[184:187], v[108:111]
	v_mfma_f32_16x16x32_bf16 v[96:99], v[140:143], v[192:195], v[96:99]
	v_mfma_f32_16x16x32_bf16 v[92:95], v[152:155], v[192:195], v[92:95]
	v_mfma_f32_16x16x32_bf16 v[80:83], v[140:143], v[204:207], v[80:83]
	v_mfma_f32_16x16x32_bf16 v[76:79], v[152:155], v[204:207], v[76:79]
	v_mfma_f32_16x16x32_bf16 v[128:131], v[144:147], v[180:183], v[128:131]
	v_mfma_f32_16x16x32_bf16 v[124:127], v[156:159], v[180:183], v[124:127]
	v_mfma_f32_16x16x32_bf16 v[112:115], v[144:147], v[188:191], v[112:115]
	v_mfma_f32_16x16x32_bf16 v[108:111], v[156:159], v[188:191], v[108:111]
	v_mfma_f32_16x16x32_bf16 v[96:99], v[144:147], v[196:199], v[96:99]
	v_mfma_f32_16x16x32_bf16 v[92:95], v[156:159], v[196:199], v[92:95]
	v_mfma_f32_16x16x32_bf16 v[80:83], v[144:147], v[208:211], v[80:83]
	v_mfma_f32_16x16x32_bf16 v[76:79], v[156:159], v[208:211], v[76:79]


	v_mfma_f32_16x16x32_bf16 v[120:123], v[160:163], v[176:179], v[120:123]
	v_mfma_f32_16x16x32_bf16 v[116:119], v[168:171], v[176:179], v[116:119]
	v_mfma_f32_16x16x32_bf16 v[104:107], v[160:163], v[184:187], v[104:107]
	v_mfma_f32_16x16x32_bf16 v[100:103], v[168:171], v[184:187], v[100:103]
	v_mfma_f32_16x16x32_bf16 v[88:91], v[160:163], v[192:195], v[88:91]
	v_mfma_f32_16x16x32_bf16 v[84:87], v[168:171], v[192:195], v[84:87]
	v_mfma_f32_16x16x32_bf16 v[72:75], v[160:163], v[204:207], v[72:75]
	v_mfma_f32_16x16x32_bf16 v[68:71], v[168:171], v[204:207], v[68:71]
	v_mfma_f32_16x16x32_bf16 v[120:123], v[164:167], v[180:183], v[120:123]
	v_mfma_f32_16x16x32_bf16 v[116:119], v[172:175], v[180:183], v[116:119]
	v_mfma_f32_16x16x32_bf16 v[104:107], v[164:167], v[188:191], v[104:107]
	v_mfma_f32_16x16x32_bf16 v[100:103], v[172:175], v[188:191], v[100:103]
	v_mfma_f32_16x16x32_bf16 v[88:91], v[164:167], v[196:199], v[88:91]
	v_mfma_f32_16x16x32_bf16 v[84:87], v[172:175], v[196:199], v[84:87]
	v_mfma_f32_16x16x32_bf16 v[72:75], v[164:167], v[208:211], v[72:75]
	v_mfma_f32_16x16x32_bf16 v[68:71], v[172:175], v[208:211], v[68:71]

	s_barrier
	s_add_i32 s50, s81, s52
	v_lshl_add_u64 v[200:201], v[200:201], 0, s[12:13]
	s_mov_b32 m0, s50
	ds_read_b128 v[176:179], v151 offset:49152
	ds_read_b128 v[180:183], v151 offset:50176
	ds_read_b128 v[184:187], v151 offset:51200
	ds_read_b128 v[188:191], v151 offset:52224
	ds_read_b128 v[192:195], v151 offset:53248
	ds_read_b128 v[196:199], v151 offset:54272
	ds_read_b128 v[204:207], v151 offset:55296
	ds_read_b128 v[208:211], v151 offset:56320
	global_load_lds_dwordx4 v[200:201], off
	s_add_i32 m0, s50, 0x2000
	s_add_u32 s48, s48, 0x80080
	v_lshl_add_u64 v[200:201], v[212:213], 0, s[12:13]
	s_addc_u32 s49, s49, 0
	s_add_i32 s50, s82, s52
	global_load_lds_dwordx4 v[200:201], off
	v_lshl_add_u64 v[200:201], s[48:49], 0, v[2:3]
	s_mov_b32 m0, s50
	s_nop 0
	global_load_lds_dwordx4 v[200:201], off
	v_lshl_add_u64 v[200:201], s[48:49], 0, v[0:1]
	s_add_i32 m0, s50, 0x2000
	s_nop 0
	global_load_lds_dwordx4 v[200:201], off


	s_waitcnt vmcnt(6)
	s_waitcnt lgkmcnt(0)
	s_barrier

	s_waitcnt lgkmcnt(0)
	v_mfma_f32_16x16x32_bf16 v[64:67], v[140:143], v[176:179], v[64:67]
	v_mfma_f32_16x16x32_bf16 v[60:63], v[152:155], v[176:179], v[60:63]
	v_mfma_f32_16x16x32_bf16 v[48:51], v[140:143], v[184:187], v[48:51]
	v_mfma_f32_16x16x32_bf16 v[44:47], v[152:155], v[184:187], v[44:47]
	v_mfma_f32_16x16x32_bf16 v[32:35], v[140:143], v[192:195], v[32:35]
	v_mfma_f32_16x16x32_bf16 v[28:31], v[152:155], v[192:195], v[28:31]
	v_mfma_f32_16x16x32_bf16 v[16:19], v[140:143], v[204:207], v[16:19]
	v_mfma_f32_16x16x32_bf16 v[12:15], v[152:155], v[204:207], v[12:15]
	v_mfma_f32_16x16x32_bf16 v[64:67], v[144:147], v[180:183], v[64:67]
	v_mfma_f32_16x16x32_bf16 v[60:63], v[156:159], v[180:183], v[60:63]
	v_mfma_f32_16x16x32_bf16 v[48:51], v[144:147], v[188:191], v[48:51]
	v_mfma_f32_16x16x32_bf16 v[44:47], v[156:159], v[188:191], v[44:47]
	v_mfma_f32_16x16x32_bf16 v[32:35], v[144:147], v[196:199], v[32:35]
	v_mfma_f32_16x16x32_bf16 v[28:31], v[156:159], v[196:199], v[28:31]
	v_mfma_f32_16x16x32_bf16 v[16:19], v[144:147], v[208:211], v[16:19]
	v_mfma_f32_16x16x32_bf16 v[12:15], v[156:159], v[208:211], v[12:15]


	v_mfma_f32_16x16x32_bf16 v[56:59], v[160:163], v[176:179], v[56:59]
	v_mfma_f32_16x16x32_bf16 v[52:55], v[168:171], v[176:179], v[52:55]
	v_mfma_f32_16x16x32_bf16 v[40:43], v[160:163], v[184:187], v[40:43]
	v_mfma_f32_16x16x32_bf16 v[36:39], v[168:171], v[184:187], v[36:39]
	v_mfma_f32_16x16x32_bf16 v[24:27], v[160:163], v[192:195], v[24:27]
	v_mfma_f32_16x16x32_bf16 v[20:23], v[168:171], v[192:195], v[20:23]
	v_mfma_f32_16x16x32_bf16 v[8:11], v[160:163], v[204:207], v[8:11]
	v_mfma_f32_16x16x32_bf16 v[4:7], v[168:171], v[204:207], v[4:7]
	v_mfma_f32_16x16x32_bf16 v[56:59], v[164:167], v[180:183], v[56:59]
	v_mfma_f32_16x16x32_bf16 v[52:55], v[172:175], v[180:183], v[52:55]
	v_mfma_f32_16x16x32_bf16 v[40:43], v[164:167], v[188:191], v[40:43]
	v_mfma_f32_16x16x32_bf16 v[36:39], v[172:175], v[188:191], v[36:39]
	v_mfma_f32_16x16x32_bf16 v[24:27], v[164:167], v[196:199], v[24:27]
	v_mfma_f32_16x16x32_bf16 v[20:23], v[172:175], v[196:199], v[20:23]
	v_mfma_f32_16x16x32_bf16 v[8:11], v[164:167], v[208:211], v[8:11]
	v_mfma_f32_16x16x32_bf16 v[4:7], v[172:175], v[208:211], v[4:7]

	s_barrier
	s_add_i32 s80, s80, 2
	s_add_u32 s46, s46, 0x100
	s_addc_u32 s47, s47, 0
	s_add_u32 s78, s78, 0x100
	s_addc_u32 s79, s79, 0
	s_cmp_gt_u32 s80, 29
	s_cbranch_scc0 .LBB0_685
	v_readlane_b32 s78, v254, 48
	v_readlane_b32 s80, v254, 50
	s_and_b64 vcc, exec, s[10:11]
	v_readlane_b32 s79, v254, 49
	v_readlane_b32 s81, v254, 51
	v_readlane_b32 s76, v254, 62
	v_readlane_b32 s77, v254, 63
	s_cbranch_vccz .LBB0_688
	s_barrier
